# RELU2 epilogue: the four row-scale LDS reads issued together with one wait
# baseline (speedup 1.0000x reference)
; #define PG8_STAGE(bufoff, gbase, voff) do { _Pragma("unroll") for (int _i = 0; _i < 2; ++_i) \
;     __builtin_amdgcn_global_load_lds((const unsigned*)((const char*)(gbase) + (voff)[_i]), (LAS unsigned*)(lds + (bufoff) + ldsw + _i * 8192), 16, 0, 0); } while (0)
; #define PG8_LDA(dst, b, h) do { _Pragma("unroll") for (int m = 0; m < 4; ++m) _Pragma("unroll") for (int k = 0; k < 2; ++k) dst[m][k] = *(const LAS bf16x8*)(lds + PG8_SA(b, h) + aoff + m * 2048 + k * 1024); } while (0)
; #define PG8_LDB(dst, b, h) do { _Pragma("unroll") for (int n = 0; n < 2; ++n) _Pragma("unroll") for (int k = 0; k < 2; ++k) dst[n][k] = *(const LAS bf16x8*)(lds + PG8_SB(b, h) + boff + n * 2048 + k * 1024); } while (0)
; #define PG8_WAIT_V(n) asm volatile("s_waitcnt vmcnt(" #n ")" ::: "memory")
; template <class Epi, class Sched>
; DI void gemm_phase(LAS unsigned char* lds, const Gemm g, const Sched& S, const Epi& E) {
;     ...
;     for (int t = 0; t < nt; t += 2) {
;       const bool last = (t == nt - 2);
;       const char* a1 = cA + (size_t)(t + 1) * kstep;
;       const char* a2 = last ? nA : cA + (size_t)(t + 2) * kstep; const char* b2 = last ? nB : cB + (size_t)(t + 2) * kstep;
;       const char* a3 = a2 + kstep; const char* b3 = b2 + kstep;
;       PG8_LDB(B0, 0, 0); PG8_SCHED; PG8_LDA(At, 0, 0); PG8_STAGE(PG8_SA(1, 1), a1 + hstep, voffA);
;       PG8_WAIT_L(8); PG8_BAR; PG8_WAIT_L(0); PG8_MMA(0, 0, At, B0); PG8_BAR; PG8_SCHED;
;       PG8_LDB(B1, 0, 1); PG8_STAGE(PG8_SB(0, 0), b2, voffB);
;       PG8_BAR; PG8_WAIT_L(0); PG8_MMA(0, 1, At, B1); PG8_BAR;
;       PG8_LDA(At, 0, 1); PG8_STAGE(PG8_SA(0, 0), a2, voffA);
;       PG8_BAR; PG8_WAIT_L(0); PG8_MMA(1, 0, At, B0); PG8_BAR; PG8_SCHED;
;       PG8_STAGE(PG8_SB(0, 1), b2 + hstep, voffB);
;       PG8_WAIT_V(6); PG8_BAR; PG8_MMA(1, 1, At, B1); PG8_BAR;
;       PG8_LDB(B0, 1, 0); PG8_SCHED; PG8_LDA(At, 1, 0); PG8_STAGE(PG8_SA(0, 1), a2 + hstep, voffA);
;       PG8_WAIT_L(8); PG8_BAR; PG8_WAIT_L(0); PG8_MMA(0, 0, At, B0); PG8_BAR; PG8_SCHED;
;       PG8_LDB(B1, 1, 1); PG8_STAGE(PG8_SB(1, 0), b3, voffB);
;       PG8_BAR; PG8_WAIT_L(0); PG8_MMA(0, 1, At, B1); PG8_BAR;
;       PG8_LDA(At, 1, 1); PG8_STAGE(PG8_SA(1, 0), a3, voffA);
;       PG8_BAR; PG8_WAIT_L(0); PG8_MMA(1, 0, At, B0); PG8_BAR; PG8_SCHED;
;       PG8_STAGE(PG8_SB(1, 1), b3 + hstep, voffB);
;       PG8_WAIT_V(6); PG8_BAR; PG8_MMA(1, 1, At, B1); PG8_BAR;
.LBB0_1829:
	s_add_u32 s16, s14, 0xfffc0080
	s_addc_u32 s17, s15, -1
	s_add_i32 s51, 0, 0x10000
	ds_read_b128 v[146:149], v224
	ds_read_b128 v[150:153], v224 offset:1024
	ds_read_b128 v[154:157], v224 offset:2048
	ds_read_b128 v[158:161], v224 offset:3072
	s_cmp_eq_u32 s50, 12
	s_cselect_b32 s19, s7, s17
	s_cselect_b32 s18, s46, s16
	s_cselect_b32 s17, s5, s49
	s_cselect_b32 s16, s47, s48
	s_add_i32 m0, s29, 0xc000
	ds_read_b128 v[162:165], v143
	ds_read_b128 v[166:169], v143 offset:1024
	ds_read_b128 v[170:173], v143 offset:2048
	ds_read_b128 v[174:177], v143 offset:3072
	ds_read_b128 v[178:181], v143 offset:4096
	ds_read_b128 v[196:199], v143 offset:5120
	ds_read_b128 v[200:203], v143 offset:6144
	ds_read_b128 v[204:207], v143 offset:7168
	global_load_lds_dwordx4 v136, s[14:15]
	s_add_i32 m0, s29, 0xe000
	s_nop 0
	global_load_lds_dwordx4 v138, s[14:15]
	s_waitcnt lgkmcnt(8)
	s_barrier
	s_waitcnt lgkmcnt(0)
	v_mfma_f32_16x16x32_bf16 v[124:127], v[146:149], v[162:165], v[124:127]
	v_mfma_f32_16x16x32_bf16 v[120:123], v[154:157], v[162:165], v[120:123]
	v_mfma_f32_16x16x32_bf16 v[112:115], v[146:149], v[170:173], v[112:115]
	v_mfma_f32_16x16x32_bf16 v[104:107], v[154:157], v[170:173], v[104:107]
	v_mfma_f32_16x16x32_bf16 v[92:95], v[146:149], v[178:181], v[92:95]
	v_mfma_f32_16x16x32_bf16 v[88:91], v[154:157], v[178:181], v[88:91]
	v_mfma_f32_16x16x32_bf16 v[80:83], v[146:149], v[200:203], v[80:83]
	v_mfma_f32_16x16x32_bf16 v[72:75], v[154:157], v[200:203], v[72:75]
	v_mfma_f32_16x16x32_bf16 v[124:127], v[150:153], v[166:169], v[124:127]
	v_mfma_f32_16x16x32_bf16 v[120:123], v[158:161], v[166:169], v[120:123]
	v_mfma_f32_16x16x32_bf16 v[112:115], v[150:153], v[174:177], v[112:115]
	v_mfma_f32_16x16x32_bf16 v[104:107], v[158:161], v[174:177], v[104:107]
	v_mfma_f32_16x16x32_bf16 v[92:95], v[150:153], v[196:199], v[92:95]
	v_mfma_f32_16x16x32_bf16 v[88:91], v[158:161], v[196:199], v[88:91]
	v_mfma_f32_16x16x32_bf16 v[80:83], v[150:153], v[204:207], v[80:83]
	v_mfma_f32_16x16x32_bf16 v[72:75], v[158:161], v[204:207], v[72:75]
	s_barrier
	s_add_i32 s54, 0, 0x14000
	s_add_i32 s51, s51, s20
	ds_read_b128 v[208:211], v225
	ds_read_b128 v[212:215], v225 offset:1024
	ds_read_b128 v[216:219], v225 offset:2048
	ds_read_b128 v[220:223], v225 offset:3072
	s_add_u32 vcc_lo, s16, s0
	s_addc_u32 vcc_hi, s17, s1
	s_mov_b32 m0, s51
	s_nop 0
	global_load_lds_dwordx4 v132, s[16:17]
	s_add_i32 m0, s51, 0x2000
	s_nop 0
	global_load_lds_dwordx4 v128, s[16:17]
	s_barrier
	s_waitcnt lgkmcnt(0)
	v_mfma_f32_16x16x32_bf16 v[116:119], v[208:211], v[162:165], v[116:119]
	v_mfma_f32_16x16x32_bf16 v[108:111], v[216:219], v[162:165], v[108:111]
	v_mfma_f32_16x16x32_bf16 v[100:103], v[208:211], v[170:173], v[100:103]
	v_mfma_f32_16x16x32_bf16 v[96:99], v[216:219], v[170:173], v[96:99]
	v_mfma_f32_16x16x32_bf16 v[84:87], v[208:211], v[178:181], v[84:87]
	v_mfma_f32_16x16x32_bf16 v[76:79], v[216:219], v[178:181], v[76:79]
	v_mfma_f32_16x16x32_bf16 v[68:71], v[208:211], v[200:203], v[68:71]
	v_mfma_f32_16x16x32_bf16 v[64:67], v[216:219], v[200:203], v[64:67]
	v_mfma_f32_16x16x32_bf16 v[116:119], v[212:215], v[166:169], v[116:119]
	v_mfma_f32_16x16x32_bf16 v[108:111], v[220:223], v[166:169], v[108:111]
	v_mfma_f32_16x16x32_bf16 v[100:103], v[212:215], v[174:177], v[100:103]
	v_mfma_f32_16x16x32_bf16 v[96:99], v[220:223], v[174:177], v[96:99]
	v_mfma_f32_16x16x32_bf16 v[84:87], v[212:215], v[196:199], v[84:87]
	v_mfma_f32_16x16x32_bf16 v[76:79], v[220:223], v[196:199], v[76:79]
	v_mfma_f32_16x16x32_bf16 v[68:71], v[212:215], v[204:207], v[68:71]
	v_mfma_f32_16x16x32_bf16 v[64:67], v[220:223], v[204:207], v[64:67]
	s_mov_b32 m0, s29
	s_add_u32 s100, s18, s0
	s_addc_u32 s101, s19, s1
	s_barrier
	ds_read_b128 v[162:165], v143 offset:16384
	ds_read_b128 v[166:169], v143 offset:17408
	ds_read_b128 v[170:173], v143 offset:18432
	ds_read_b128 v[174:177], v143 offset:19456
	ds_read_b128 v[178:181], v143 offset:20480
	ds_read_b128 v[196:199], v143 offset:21504
	ds_read_b128 v[200:203], v143 offset:22528
	ds_read_b128 v[204:207], v143 offset:23552
	global_load_lds_dwordx4 v134, s[18:19]
	s_mov_b32 m0, s34
	s_nop 0
	global_load_lds_dwordx4 v130, s[18:19]
	s_barrier
	s_waitcnt lgkmcnt(0)
	v_mfma_f32_16x16x32_bf16 v[60:63], v[146:149], v[162:165], v[60:63]
	v_mfma_f32_16x16x32_bf16 v[56:59], v[154:157], v[162:165], v[56:59]
	v_mfma_f32_16x16x32_bf16 v[48:51], v[146:149], v[170:173], v[48:51]
	v_mfma_f32_16x16x32_bf16 v[40:43], v[154:157], v[170:173], v[40:43]
	v_mfma_f32_16x16x32_bf16 v[28:31], v[146:149], v[178:181], v[28:31]
	v_mfma_f32_16x16x32_bf16 v[24:27], v[154:157], v[178:181], v[24:27]
	v_mfma_f32_16x16x32_bf16 v[16:19], v[146:149], v[200:203], v[16:19]
	v_mfma_f32_16x16x32_bf16 v[8:11], v[154:157], v[200:203], v[8:11]
	v_mfma_f32_16x16x32_bf16 v[60:63], v[150:153], v[166:169], v[60:63]
	v_mfma_f32_16x16x32_bf16 v[56:59], v[158:161], v[166:169], v[56:59]
	v_mfma_f32_16x16x32_bf16 v[48:51], v[150:153], v[174:177], v[48:51]
	v_mfma_f32_16x16x32_bf16 v[40:43], v[158:161], v[174:177], v[40:43]
	v_mfma_f32_16x16x32_bf16 v[28:31], v[150:153], v[196:199], v[28:31]
	v_mfma_f32_16x16x32_bf16 v[24:27], v[158:161], v[196:199], v[24:27]
	v_mfma_f32_16x16x32_bf16 v[16:19], v[150:153], v[204:207], v[16:19]
	v_mfma_f32_16x16x32_bf16 v[8:11], v[158:161], v[204:207], v[8:11]
	s_barrier
	s_add_u32 s52, s16, 0x40000
	s_addc_u32 s53, s17, 0
	s_add_i32 s51, s54, s20
	s_mov_b32 m0, s51
	s_nop 0
	global_load_lds_dwordx4 v132, s[52:53]
	s_add_i32 m0, s51, 0x2000
	s_nop 0
	global_load_lds_dwordx4 v128, s[52:53]
	s_waitcnt vmcnt(6)
	s_barrier
; #define PG8_STAGE(bufoff, gbase, voff) do { _Pragma("unroll") for (int _i = 0; _i < 2; ++_i) \
;     __builtin_amdgcn_global_load_lds((const unsigned*)((const char*)(gbase) + (voff)[_i]), (LAS unsigned*)(lds + (bufoff) + ldsw + _i * 8192), 16, 0, 0); } while (0)
; #define PG8_LDA(dst, b, h) do { _Pragma("unroll") for (int m = 0; m < 4; ++m) _Pragma("unroll") for (int k = 0; k < 2; ++k) dst[m][k] = *(const LAS bf16x8*)(lds + PG8_SA(b, h) + aoff + m * 2048 + k * 1024); } while (0)
; #define PG8_LDB(dst, b, h) do { _Pragma("unroll") for (int n = 0; n < 2; ++n) _Pragma("unroll") for (int k = 0; k < 2; ++k) dst[n][k] = *(const LAS bf16x8*)(lds + PG8_SB(b, h) + boff + n * 2048 + k * 1024); } while (0)
; #define PG8_WAIT_V(n) asm volatile("s_waitcnt vmcnt(" #n ")" ::: "memory")
; template <class Epi, class Sched>
; DI void gemm_phase(LAS unsigned char* lds, const Gemm g, const Sched& S, const Epi& E) {
;     ...
;     for (int t = 0; t < nt; t += 2) {
;       const bool last = (t == nt - 2);
;       const char* a1 = cA + (size_t)(t + 1) * kstep;
;       const char* a2 = last ? nA : cA + (size_t)(t + 2) * kstep; const char* b2 = last ? nB : cB + (size_t)(t + 2) * kstep;
;       const char* a3 = a2 + kstep; const char* b3 = b2 + kstep;
;       PG8_LDB(B0, 0, 0); PG8_SCHED; PG8_LDA(At, 0, 0); PG8_STAGE(PG8_SA(1, 1), a1 + hstep, voffA);
;       PG8_WAIT_L(8); PG8_BAR; PG8_WAIT_L(0); PG8_MMA(0, 0, At, B0); PG8_BAR; PG8_SCHED;
;       PG8_LDB(B1, 0, 1); PG8_STAGE(PG8_SB(0, 0), b2, voffB);
;       PG8_BAR; PG8_WAIT_L(0); PG8_MMA(0, 1, At, B1); PG8_BAR;
;       PG8_LDA(At, 0, 1); PG8_STAGE(PG8_SA(0, 0), a2, voffA);
;       PG8_BAR; PG8_WAIT_L(0); PG8_MMA(1, 0, At, B0); PG8_BAR; PG8_SCHED;
;       PG8_STAGE(PG8_SB(0, 1), b2 + hstep, voffB);
;       PG8_WAIT_V(6); PG8_BAR; PG8_MMA(1, 1, At, B1); PG8_BAR;
;       PG8_LDB(B0, 1, 0); PG8_SCHED; PG8_LDA(At, 1, 0); PG8_STAGE(PG8_SA(0, 1), a2 + hstep, voffA);
;       PG8_WAIT_L(8); PG8_BAR; PG8_WAIT_L(0); PG8_MMA(0, 0, At, B0); PG8_BAR; PG8_SCHED;
;       PG8_LDB(B1, 1, 1); PG8_STAGE(PG8_SB(1, 0), b3, voffB);
;       PG8_BAR; PG8_WAIT_L(0); PG8_MMA(0, 1, At, B1); PG8_BAR;
;       PG8_LDA(At, 1, 1); PG8_STAGE(PG8_SA(1, 0), a3, voffA);
;       PG8_BAR; PG8_WAIT_L(0); PG8_MMA(1, 0, At, B0); PG8_BAR; PG8_SCHED;
;       PG8_STAGE(PG8_SB(1, 1), b3 + hstep, voffB);
;       PG8_WAIT_V(6); PG8_BAR; PG8_MMA(1, 1, At, B1); PG8_BAR;
	v_mfma_f32_16x16x32_bf16 v[52:55], v[208:211], v[162:165], v[52:55]
	v_mfma_f32_16x16x32_bf16 v[44:47], v[216:219], v[162:165], v[44:47]
	v_mfma_f32_16x16x32_bf16 v[36:39], v[208:211], v[170:173], v[36:39]
	v_mfma_f32_16x16x32_bf16 v[32:35], v[216:219], v[170:173], v[32:35]
	v_mfma_f32_16x16x32_bf16 v[20:23], v[208:211], v[178:181], v[20:23]
	v_mfma_f32_16x16x32_bf16 v[12:15], v[216:219], v[178:181], v[12:15]
	v_mfma_f32_16x16x32_bf16 v[4:7], v[208:211], v[200:203], v[4:7]
	v_mfma_f32_16x16x32_bf16 v[0:3], v[216:219], v[200:203], v[0:3]
	v_mfma_f32_16x16x32_bf16 v[52:55], v[212:215], v[166:169], v[52:55]
	v_mfma_f32_16x16x32_bf16 v[44:47], v[220:223], v[166:169], v[44:47]
	v_mfma_f32_16x16x32_bf16 v[36:39], v[212:215], v[174:177], v[36:39]
	v_mfma_f32_16x16x32_bf16 v[32:35], v[220:223], v[174:177], v[32:35]
	v_mfma_f32_16x16x32_bf16 v[20:23], v[212:215], v[196:199], v[20:23]
	v_mfma_f32_16x16x32_bf16 v[12:15], v[220:223], v[196:199], v[12:15]
	v_mfma_f32_16x16x32_bf16 v[4:7], v[212:215], v[204:207], v[4:7]
	v_mfma_f32_16x16x32_bf16 v[0:3], v[220:223], v[204:207], v[0:3]
	s_add_i32 s51, 0, 0x18000
	s_barrier
	ds_read_b128 v[146:149], v226
	ds_read_b128 v[150:153], v226 offset:1024
	ds_read_b128 v[154:157], v226 offset:2048
	ds_read_b128 v[158:161], v226 offset:3072
	s_add_u32 s18, s18, 0x40000
	s_addc_u32 s19, s19, 0
	s_mov_b32 m0, s35
	ds_read_b128 v[162:165], v143 offset:32768
	ds_read_b128 v[166:169], v143 offset:33792
	ds_read_b128 v[170:173], v143 offset:34816
	ds_read_b128 v[174:177], v143 offset:35840
	ds_read_b128 v[178:181], v143 offset:36864
	ds_read_b128 v[196:199], v143 offset:37888
	ds_read_b128 v[200:203], v143 offset:38912
	ds_read_b128 v[204:207], v143 offset:39936
	global_load_lds_dwordx4 v134, s[18:19]
	s_mov_b32 m0, s38
	s_nop 0
	global_load_lds_dwordx4 v130, s[18:19]
	s_waitcnt lgkmcnt(8)
	s_barrier
	s_waitcnt lgkmcnt(0)
	v_mfma_f32_16x16x32_bf16 v[124:127], v[146:149], v[162:165], v[124:127]
	v_mfma_f32_16x16x32_bf16 v[120:123], v[154:157], v[162:165], v[120:123]
	v_mfma_f32_16x16x32_bf16 v[112:115], v[146:149], v[170:173], v[112:115]
	v_mfma_f32_16x16x32_bf16 v[104:107], v[154:157], v[170:173], v[104:107]
	v_mfma_f32_16x16x32_bf16 v[92:95], v[146:149], v[178:181], v[92:95]
	v_mfma_f32_16x16x32_bf16 v[88:91], v[154:157], v[178:181], v[88:91]
	v_mfma_f32_16x16x32_bf16 v[80:83], v[146:149], v[200:203], v[80:83]
	v_mfma_f32_16x16x32_bf16 v[72:75], v[154:157], v[200:203], v[72:75]
	v_mfma_f32_16x16x32_bf16 v[124:127], v[150:153], v[166:169], v[124:127]
	v_mfma_f32_16x16x32_bf16 v[120:123], v[158:161], v[166:169], v[120:123]
	v_mfma_f32_16x16x32_bf16 v[112:115], v[150:153], v[174:177], v[112:115]
	v_mfma_f32_16x16x32_bf16 v[104:107], v[158:161], v[174:177], v[104:107]
	v_mfma_f32_16x16x32_bf16 v[92:95], v[150:153], v[196:199], v[92:95]
	v_mfma_f32_16x16x32_bf16 v[88:91], v[158:161], v[196:199], v[88:91]
	v_mfma_f32_16x16x32_bf16 v[80:83], v[150:153], v[204:207], v[80:83]
	v_mfma_f32_16x16x32_bf16 v[72:75], v[158:161], v[204:207], v[72:75]
	s_barrier
	s_add_i32 s18, 0, 0x1c000
	s_add_i32 s19, s51, s20
	s_mov_b32 m0, s19
	ds_read_b128 v[208:211], v227
	ds_read_b128 v[212:215], v227 offset:1024
	ds_read_b128 v[216:219], v227 offset:2048
	ds_read_b128 v[220:223], v227 offset:3072
	global_load_lds_dwordx4 v132, vcc
	s_add_i32 m0, s19, 0x2000
	s_nop 0
	global_load_lds_dwordx4 v128, vcc
	s_barrier
	s_waitcnt lgkmcnt(0)
	v_mfma_f32_16x16x32_bf16 v[116:119], v[208:211], v[162:165], v[116:119]
	v_mfma_f32_16x16x32_bf16 v[108:111], v[216:219], v[162:165], v[108:111]
	v_mfma_f32_16x16x32_bf16 v[100:103], v[208:211], v[170:173], v[100:103]
	v_mfma_f32_16x16x32_bf16 v[96:99], v[216:219], v[170:173], v[96:99]
	v_mfma_f32_16x16x32_bf16 v[84:87], v[208:211], v[178:181], v[84:87]
	v_mfma_f32_16x16x32_bf16 v[76:79], v[216:219], v[178:181], v[76:79]
	v_mfma_f32_16x16x32_bf16 v[68:71], v[208:211], v[200:203], v[68:71]
	v_mfma_f32_16x16x32_bf16 v[64:67], v[216:219], v[200:203], v[64:67]
	v_mfma_f32_16x16x32_bf16 v[116:119], v[212:215], v[166:169], v[116:119]
	v_mfma_f32_16x16x32_bf16 v[108:111], v[220:223], v[166:169], v[108:111]
	v_mfma_f32_16x16x32_bf16 v[100:103], v[212:215], v[174:177], v[100:103]
	v_mfma_f32_16x16x32_bf16 v[96:99], v[220:223], v[174:177], v[96:99]
	v_mfma_f32_16x16x32_bf16 v[84:87], v[212:215], v[196:199], v[84:87]
	v_mfma_f32_16x16x32_bf16 v[76:79], v[220:223], v[196:199], v[76:79]
	v_mfma_f32_16x16x32_bf16 v[68:71], v[212:215], v[204:207], v[68:71]
	v_mfma_f32_16x16x32_bf16 v[64:67], v[220:223], v[204:207], v[64:67]
	s_mov_b32 m0, s40
	s_barrier
	ds_read_b128 v[162:165], v143 offset:49152
	ds_read_b128 v[166:169], v143 offset:50176
	ds_read_b128 v[170:173], v143 offset:51200
	ds_read_b128 v[174:177], v143 offset:52224
	ds_read_b128 v[178:181], v143 offset:53248
	ds_read_b128 v[196:199], v143 offset:54272
	ds_read_b128 v[200:203], v143 offset:55296
	ds_read_b128 v[204:207], v143 offset:56320
	global_load_lds_dwordx4 v134, s[100:101]
	s_mov_b32 m0, s41
	s_nop 0
	global_load_lds_dwordx4 v130, s[100:101]
	s_barrier
	s_waitcnt lgkmcnt(0)
	v_mfma_f32_16x16x32_bf16 v[60:63], v[146:149], v[162:165], v[60:63]
	v_mfma_f32_16x16x32_bf16 v[56:59], v[154:157], v[162:165], v[56:59]
	v_mfma_f32_16x16x32_bf16 v[48:51], v[146:149], v[170:173], v[48:51]
	v_mfma_f32_16x16x32_bf16 v[40:43], v[154:157], v[170:173], v[40:43]
	v_mfma_f32_16x16x32_bf16 v[28:31], v[146:149], v[178:181], v[28:31]
	v_mfma_f32_16x16x32_bf16 v[24:27], v[154:157], v[178:181], v[24:27]
	v_mfma_f32_16x16x32_bf16 v[16:19], v[146:149], v[200:203], v[16:19]
	v_mfma_f32_16x16x32_bf16 v[8:11], v[154:157], v[200:203], v[8:11]
	v_mfma_f32_16x16x32_bf16 v[60:63], v[150:153], v[166:169], v[60:63]
	v_mfma_f32_16x16x32_bf16 v[56:59], v[158:161], v[166:169], v[56:59]
	v_mfma_f32_16x16x32_bf16 v[48:51], v[150:153], v[174:177], v[48:51]
	v_mfma_f32_16x16x32_bf16 v[40:43], v[158:161], v[174:177], v[40:43]
	v_mfma_f32_16x16x32_bf16 v[28:31], v[150:153], v[196:199], v[28:31]
	v_mfma_f32_16x16x32_bf16 v[24:27], v[158:161], v[196:199], v[24:27]
	v_mfma_f32_16x16x32_bf16 v[16:19], v[150:153], v[204:207], v[16:19]
	v_mfma_f32_16x16x32_bf16 v[8:11], v[158:161], v[204:207], v[8:11]
	s_barrier
;   DI void operator()(const f32x4 (&acc)[2][2][4][2], const pg8::Unit& u, int wr, int wc, int fr_, int fq_) const {
;     ...
;         const int rl = ai * 128 + wr * 64 + m * 16 + fr;
;         const int token = u.pm * 256 + rl;
;         float rinv = 1.f;
;         if (EPI != EPI_RESID) rinv = rinv_tab[slot * 256 + rl];
;     ...
;             } else {
;               if (n == 0) {
;                 const f32x4 v1 = acc[ai][bj][m][1];
;                 u32x4 o4;
;                 { const float t0 = fmaxf(v[0], 0.f) * rinv, t1 = fmaxf(v[1], 0.f) * rinv, t2 = fmaxf(v[2], 0.f) * rinv, t3 = fmaxf(v[3], 0.f) * rinv;
;                   o4.x = pack2(t0 * t0, t1 * t1); o4.y = pack2(t2 * t2, t3 * t3); }
;                 { const float t0 = fmaxf(v1[0], 0.f) * rinv, t1 = fmaxf(v1[1], 0.f) * rinv, t2 = fmaxf(v1[2], 0.f) * rinv, t3 = fmaxf(v1[3], 0.f) * rinv;
;                   o4.z = pack2(t0 * t0, t1 * t1); o4.w = pack2(t2 * t2, t3 * t3); }
;                 *(u32x4*)((u16*)big + (size_t)token * 4096 + u.pn * 256 + bj * 128 + wc * 32 + 8 * fq) = o4;
;               }
	s_add_u32 s16, s16, 0x40080
	s_addc_u32 s17, s17, 0
	s_add_i32 s18, s18, s20
	s_mov_b32 m0, s18
	s_nop 0
	global_load_lds_dwordx4 v132, s[16:17]
	s_add_i32 m0, s18, 0x2000
	s_nop 0
	global_load_lds_dwordx4 v128, s[16:17]
	s_waitcnt vmcnt(6)
	s_barrier
	v_mfma_f32_16x16x32_bf16 v[52:55], v[208:211], v[162:165], v[52:55]
	v_mfma_f32_16x16x32_bf16 v[44:47], v[216:219], v[162:165], v[44:47]
	v_mfma_f32_16x16x32_bf16 v[36:39], v[208:211], v[170:173], v[36:39]
	v_mfma_f32_16x16x32_bf16 v[32:35], v[216:219], v[170:173], v[32:35]
	v_mfma_f32_16x16x32_bf16 v[20:23], v[208:211], v[178:181], v[20:23]
	v_mfma_f32_16x16x32_bf16 v[12:15], v[216:219], v[178:181], v[12:15]
	v_mfma_f32_16x16x32_bf16 v[4:7], v[208:211], v[200:203], v[4:7]
	v_mfma_f32_16x16x32_bf16 v[0:3], v[216:219], v[200:203], v[0:3]
	v_mfma_f32_16x16x32_bf16 v[52:55], v[212:215], v[166:169], v[52:55]
	v_mfma_f32_16x16x32_bf16 v[44:47], v[220:223], v[166:169], v[44:47]
	v_mfma_f32_16x16x32_bf16 v[36:39], v[212:215], v[174:177], v[36:39]
	v_mfma_f32_16x16x32_bf16 v[32:35], v[220:223], v[174:177], v[32:35]
	v_mfma_f32_16x16x32_bf16 v[20:23], v[212:215], v[196:199], v[20:23]
	v_mfma_f32_16x16x32_bf16 v[12:15], v[220:223], v[196:199], v[12:15]
	v_mfma_f32_16x16x32_bf16 v[4:7], v[212:215], v[204:207], v[4:7]
	v_mfma_f32_16x16x32_bf16 v[0:3], v[220:223], v[204:207], v[0:3]
	s_add_i32 s50, s50, 2
	s_add_u32 s14, s14, 0x100
	s_addc_u32 s15, s15, 0
	s_add_u32 s48, s48, 0x100
	s_addc_u32 s49, s49, 0
	s_cmp_gt_u32 s50, 13
	s_barrier
	s_cbranch_scc0 .LBB0_1829
	v_mov_b32_e32 v144, v182
	s_lshl_b32 s5, s43, 10
	s_add_i32 s5, s5, 0
	v_and_or_b32 v141, v144, 15, s39
	v_lshl_add_u32 v140, s44, 8, v141
	v_lshl_add_u32 v141, v141, 2, s5
	v_add_u32_e32 v146, 0x20000, v141
	ds_read2_b32 v[148:149], v146 offset1:16
	ds_read2_b32 v[160:161], v146 offset0:32 offset1:48
	ds_read2_b32 v[162:163], v146 offset0:128 offset1:144
	ds_read2_b32 v[164:165], v146 offset0:160 offset1:176
	v_max_f32_e32 v124, 0, v124
	v_max_f32_e32 v125, 0, v125
	v_max_f32_e32 v126, 0, v126
	v_max_f32_e32 v127, 0, v127
	v_max_f32_e32 v120, 0, v120
	v_max_f32_e32 v121, 0, v121
	s_waitcnt lgkmcnt(0)
	v_pk_mul_f32 v[124:125], v[124:125], v[148:149] op_sel_hi:[1,0]
	v_pk_mul_f32 v[126:127], v[126:127], v[148:149] op_sel_hi:[1,0]
	v_pk_mul_f32 v[120:121], v[120:121], v[148:149] op_sel_hi:[1,0]
	v_pk_mul_f32 v[124:125], v[124:125], v[124:125]
	v_pk_mul_f32 v[126:127], v[126:127], v[126:127]
	v_max_f32_e32 v122, 0, v122
	v_max_f32_e32 v123, 0, v123
	v_pk_mul_f32 v[120:121], v[120:121], v[120:121]
	v_max_f32_e32 v116, 0, v116
	v_max_f32_e32 v117, 0, v117
	v_max_f32_e32 v118, 0, v118
	v_max_f32_e32 v119, 0, v119
	v_max_f32_e32 v108, 0, v108
	v_max_f32_e32 v109, 0, v109
	s_lshl_b32 s14, s45, 8
	v_ashrrev_i32_e32 v141, 31, v140
	v_cvt_pk_bf16_f32 v124, v124, v125
	v_cvt_pk_bf16_f32 v125, v126, v127
	v_cvt_pk_bf16_f32 v126, v120, v121
	v_pk_mul_f32 v[120:121], v[122:123], v[148:149] op_sel_hi:[1,0]
	v_pk_mul_f32 v[116:117], v[116:117], v[148:149] op_sel_hi:[1,0]
	v_pk_mul_f32 v[118:119], v[118:119], v[148:149] op_sel_hi:[1,0]
	v_pk_mul_f32 v[108:109], v[108:109], v[148:149] op_sel_hi:[1,0]
	s_ashr_i32 s15, s14, 31
	v_lshlrev_b64 v[150:151], 13, v[140:141]
	v_pk_mul_f32 v[120:121], v[120:121], v[120:121]
	v_pk_mul_f32 v[116:117], v[116:117], v[116:117]
	v_pk_mul_f32 v[118:119], v[118:119], v[118:119]
	v_max_f32_e32 v110, 0, v110
	v_max_f32_e32 v111, 0, v111
	v_pk_mul_f32 v[108:109], v[108:109], v[108:109]
	v_cvt_pk_bf16_f32 v127, v120, v121
	v_lshl_add_u64 v[120:121], s[2:3], 0, v[150:151]
	s_lshl_b64 s[14:15], s[14:15], 1
	v_cvt_pk_bf16_f32 v116, v116, v117
	v_cvt_pk_bf16_f32 v117, v118, v119
	v_cvt_pk_bf16_f32 v118, v108, v109
	v_pk_mul_f32 v[108:109], v[110:111], v[148:149] op_sel_hi:[1,0]
	v_lshl_add_u64 v[120:121], v[120:121], 0, s[14:15]
	v_pk_mul_f32 v[108:109], v[108:109], v[108:109]
	v_lshl_add_u64 v[120:121], v[120:121], 0, s[24:25]
	v_and_b32_e32 v144, 48, v144
	v_cvt_pk_bf16_f32 v119, v108, v109
	v_add_u32_e32 v108, 16, v140
	v_lshl_add_u64 v[120:121], v[120:121], 0, v[144:145]
	v_ashrrev_i32_e32 v109, 31, v108
	global_store_dwordx4 v[120:121], v[116:119], off offset:256
	v_max_f32_e32 v100, 0, v100
	v_max_f32_e32 v101, 0, v101
	v_lshlrev_b64 v[116:117], 13, v[108:109]
	v_max_f32_e32 v108, v112, v112
	v_mov_b32_e32 v112, v149
	v_max_f32_e32 v102, 0, v102
	v_max_f32_e32 v103, 0, v103
	v_max_f32_e32 v96, 0, v96
	v_max_f32_e32 v97, 0, v97
	v_pk_mul_f32 v[100:101], v[100:101], v[112:113] op_sel_hi:[1,0]
	v_pk_mul_f32 v[102:103], v[102:103], v[112:113] op_sel_hi:[1,0]
	v_pk_mul_f32 v[96:97], v[96:97], v[112:113] op_sel_hi:[1,0]
	v_pk_mul_f32 v[100:101], v[100:101], v[100:101]
	v_pk_mul_f32 v[102:103], v[102:103], v[102:103]
	v_max_f32_e32 v98, 0, v98
	v_max_f32_e32 v99, 0, v99
	v_pk_mul_f32 v[96:97], v[96:97], v[96:97]
	v_cvt_pk_bf16_f32 v100, v100, v101
	v_cvt_pk_bf16_f32 v101, v102, v103
	v_cvt_pk_bf16_f32 v102, v96, v97
	v_pk_mul_f32 v[96:97], v[98:99], v[112:113] op_sel_hi:[1,0]
	v_max_f32_e32 v92, 0, v92
	v_max_f32_e32 v93, 0, v93
	v_max_f32_e32 v94, 0, v94
	v_max_f32_e32 v95, 0, v95
	v_max_f32_e32 v88, 0, v88
	v_max_f32_e32 v89, 0, v89
	v_pk_mul_f32 v[96:97], v[96:97], v[96:97]
	v_pk_mul_f32 v[92:93], v[92:93], v[160:161] op_sel_hi:[1,0]
	v_pk_mul_f32 v[94:95], v[94:95], v[160:161] op_sel_hi:[1,0]
	v_pk_mul_f32 v[88:89], v[88:89], v[160:161] op_sel_hi:[1,0]
	v_cvt_pk_bf16_f32 v103, v96, v97
	v_add_u32_e32 v96, 32, v140
	v_pk_mul_f32 v[92:93], v[92:93], v[92:93]
	v_pk_mul_f32 v[94:95], v[94:95], v[94:95]
	v_max_f32_e32 v90, 0, v90
	v_max_f32_e32 v91, 0, v91
	v_pk_mul_f32 v[88:89], v[88:89], v[88:89]
	v_max_f32_e32 v84, 0, v84
;   DI void operator()(const f32x4 (&acc)[2][2][4][2], const pg8::Unit& u, int wr, int wc, int fr_, int fq_) const {
;     ...
;             } else {
;               if (n == 0) {
;                 const f32x4 v1 = acc[ai][bj][m][1];
;                 u32x4 o4;
;                 { const float t0 = fmaxf(v[0], 0.f) * rinv, t1 = fmaxf(v[1], 0.f) * rinv, t2 = fmaxf(v[2], 0.f) * rinv, t3 = fmaxf(v[3], 0.f) * rinv;
;                   o4.x = pack2(t0 * t0, t1 * t1); o4.y = pack2(t2 * t2, t3 * t3); }
;                 { const float t0 = fmaxf(v1[0], 0.f) * rinv, t1 = fmaxf(v1[1], 0.f) * rinv, t2 = fmaxf(v1[2], 0.f) * rinv, t3 = fmaxf(v1[3], 0.f) * rinv;
;                   o4.z = pack2(t0 * t0, t1 * t1); o4.w = pack2(t2 * t2, t3 * t3); }
;                 *(u32x4*)((u16*)big + (size_t)token * 4096 + u.pn * 256 + bj * 128 + wc * 32 + 8 * fq) = o4;
;               }
	v_max_f32_e32 v85, 0, v85
	v_max_f32_e32 v86, 0, v86
	v_max_f32_e32 v87, 0, v87
	v_max_f32_e32 v76, 0, v76
	v_max_f32_e32 v77, 0, v77
	v_ashrrev_i32_e32 v97, 31, v96
	v_cvt_pk_bf16_f32 v92, v92, v93
	v_cvt_pk_bf16_f32 v93, v94, v95
	v_cvt_pk_bf16_f32 v94, v88, v89
	v_pk_mul_f32 v[88:89], v[90:91], v[160:161] op_sel_hi:[1,0]
	v_pk_mul_f32 v[84:85], v[84:85], v[160:161] op_sel_hi:[1,0]
	v_pk_mul_f32 v[86:87], v[86:87], v[160:161] op_sel_hi:[1,0]
	v_pk_mul_f32 v[76:77], v[76:77], v[160:161] op_sel_hi:[1,0]
	v_lshlrev_b64 v[96:97], 13, v[96:97]
	v_pk_mul_f32 v[88:89], v[88:89], v[88:89]
	v_pk_mul_f32 v[84:85], v[84:85], v[84:85]
	v_pk_mul_f32 v[86:87], v[86:87], v[86:87]
	v_max_f32_e32 v78, 0, v78
	v_max_f32_e32 v79, 0, v79
	v_pk_mul_f32 v[76:77], v[76:77], v[76:77]
	v_cvt_pk_bf16_f32 v95, v88, v89
	v_lshl_add_u64 v[88:89], s[2:3], 0, v[96:97]
	v_cvt_pk_bf16_f32 v84, v84, v85
	v_cvt_pk_bf16_f32 v85, v86, v87
	v_cvt_pk_bf16_f32 v86, v76, v77
	v_pk_mul_f32 v[76:77], v[78:79], v[160:161] op_sel_hi:[1,0]
	v_lshl_add_u64 v[88:89], v[88:89], 0, s[14:15]
	v_pk_mul_f32 v[76:77], v[76:77], v[76:77]
	v_lshl_add_u64 v[88:89], v[88:89], 0, s[24:25]
	v_cvt_pk_bf16_f32 v87, v76, v77
	v_add_u32_e32 v76, 48, v140
	v_lshl_add_u64 v[88:89], v[88:89], 0, v[144:145]
	v_ashrrev_i32_e32 v77, 31, v76
	global_store_dwordx4 v[88:89], v[84:87], off offset:256
	v_max_f32_e32 v68, 0, v68
	v_max_f32_e32 v69, 0, v69
	v_lshlrev_b64 v[84:85], 13, v[76:77]
	v_max_f32_e32 v76, v80, v80
	v_mov_b32_e32 v80, v161
	v_max_f32_e32 v70, 0, v70
	v_max_f32_e32 v71, 0, v71
	v_max_f32_e32 v64, 0, v64
	v_max_f32_e32 v65, 0, v65
	v_pk_mul_f32 v[68:69], v[68:69], v[80:81] op_sel_hi:[1,0]
	v_pk_mul_f32 v[70:71], v[70:71], v[80:81] op_sel_hi:[1,0]
	v_pk_mul_f32 v[64:65], v[64:65], v[80:81] op_sel_hi:[1,0]
	v_pk_mul_f32 v[68:69], v[68:69], v[68:69]
	v_pk_mul_f32 v[70:71], v[70:71], v[70:71]
	v_max_f32_e32 v66, 0, v66
	v_max_f32_e32 v67, 0, v67
	v_pk_mul_f32 v[64:65], v[64:65], v[64:65]
	v_cvt_pk_bf16_f32 v68, v68, v69
	v_cvt_pk_bf16_f32 v69, v70, v71
	v_cvt_pk_bf16_f32 v70, v64, v65
	v_pk_mul_f32 v[64:65], v[66:67], v[80:81] op_sel_hi:[1,0]
	v_max_f32_e32 v60, 0, v60
	v_max_f32_e32 v61, 0, v61
	v_max_f32_e32 v62, 0, v62
	v_max_f32_e32 v63, 0, v63
	v_max_f32_e32 v56, 0, v56
	v_max_f32_e32 v57, 0, v57
	v_pk_mul_f32 v[64:65], v[64:65], v[64:65]
	v_pk_mul_f32 v[60:61], v[60:61], v[162:163] op_sel_hi:[1,0]
	v_pk_mul_f32 v[62:63], v[62:63], v[162:163] op_sel_hi:[1,0]
	v_pk_mul_f32 v[56:57], v[56:57], v[162:163] op_sel_hi:[1,0]
	v_cvt_pk_bf16_f32 v71, v64, v65
	v_add_u32_e32 v64, 0x80, v140
	v_pk_mul_f32 v[60:61], v[60:61], v[60:61]
	v_pk_mul_f32 v[62:63], v[62:63], v[62:63]
	v_max_f32_e32 v58, 0, v58
	v_max_f32_e32 v59, 0, v59
	v_pk_mul_f32 v[56:57], v[56:57], v[56:57]
	v_max_f32_e32 v52, 0, v52
	v_max_f32_e32 v53, 0, v53
	v_max_f32_e32 v54, 0, v54
	v_max_f32_e32 v55, 0, v55
	v_max_f32_e32 v44, 0, v44
	v_max_f32_e32 v45, 0, v45
	v_ashrrev_i32_e32 v65, 31, v64
	v_cvt_pk_bf16_f32 v60, v60, v61
	v_cvt_pk_bf16_f32 v61, v62, v63
	v_cvt_pk_bf16_f32 v62, v56, v57
	v_pk_mul_f32 v[56:57], v[58:59], v[162:163] op_sel_hi:[1,0]
	v_pk_mul_f32 v[52:53], v[52:53], v[162:163] op_sel_hi:[1,0]
	v_pk_mul_f32 v[54:55], v[54:55], v[162:163] op_sel_hi:[1,0]
	v_pk_mul_f32 v[44:45], v[44:45], v[162:163] op_sel_hi:[1,0]
	v_lshlrev_b64 v[64:65], 13, v[64:65]
	v_pk_mul_f32 v[56:57], v[56:57], v[56:57]
	v_pk_mul_f32 v[52:53], v[52:53], v[52:53]
	v_pk_mul_f32 v[54:55], v[54:55], v[54:55]
	v_max_f32_e32 v46, 0, v46
	v_max_f32_e32 v47, 0, v47
	v_pk_mul_f32 v[44:45], v[44:45], v[44:45]
	v_cvt_pk_bf16_f32 v63, v56, v57
	v_lshl_add_u64 v[56:57], s[2:3], 0, v[64:65]
	v_cvt_pk_bf16_f32 v52, v52, v53
	v_cvt_pk_bf16_f32 v53, v54, v55
	v_cvt_pk_bf16_f32 v54, v44, v45
	v_pk_mul_f32 v[44:45], v[46:47], v[162:163] op_sel_hi:[1,0]
	v_lshl_add_u64 v[56:57], v[56:57], 0, s[14:15]
	v_pk_mul_f32 v[44:45], v[44:45], v[44:45]
	v_lshl_add_u64 v[56:57], v[56:57], 0, s[24:25]
	v_cvt_pk_bf16_f32 v55, v44, v45
	v_add_u32_e32 v44, 0x90, v140
	v_lshl_add_u64 v[56:57], v[56:57], 0, v[144:145]
	v_ashrrev_i32_e32 v45, 31, v44
	global_store_dwordx4 v[56:57], v[52:55], off offset:256
	v_max_f32_e32 v36, 0, v36
	v_max_f32_e32 v37, 0, v37
	v_lshlrev_b64 v[52:53], 13, v[44:45]
	v_max_f32_e32 v44, v48, v48
	v_mov_b32_e32 v48, v163
	v_max_f32_e32 v38, 0, v38
	v_max_f32_e32 v39, 0, v39
	v_max_f32_e32 v32, 0, v32
	v_max_f32_e32 v33, 0, v33
	v_pk_mul_f32 v[36:37], v[36:37], v[48:49] op_sel_hi:[1,0]
	v_pk_mul_f32 v[38:39], v[38:39], v[48:49] op_sel_hi:[1,0]
	v_pk_mul_f32 v[32:33], v[32:33], v[48:49] op_sel_hi:[1,0]
	v_pk_mul_f32 v[36:37], v[36:37], v[36:37]
	v_pk_mul_f32 v[38:39], v[38:39], v[38:39]
	v_max_f32_e32 v34, 0, v34
	v_max_f32_e32 v35, 0, v35
	v_pk_mul_f32 v[32:33], v[32:33], v[32:33]
	v_cvt_pk_bf16_f32 v36, v36, v37
	v_cvt_pk_bf16_f32 v37, v38, v39
	v_cvt_pk_bf16_f32 v38, v32, v33
	v_pk_mul_f32 v[32:33], v[34:35], v[48:49] op_sel_hi:[1,0]
	v_max_f32_e32 v28, 0, v28
	v_max_f32_e32 v29, 0, v29
	v_max_f32_e32 v30, 0, v30
	v_max_f32_e32 v31, 0, v31
	v_max_f32_e32 v24, 0, v24
	v_max_f32_e32 v25, 0, v25
	v_pk_mul_f32 v[32:33], v[32:33], v[32:33]
	v_pk_mul_f32 v[28:29], v[28:29], v[164:165] op_sel_hi:[1,0]
	v_pk_mul_f32 v[30:31], v[30:31], v[164:165] op_sel_hi:[1,0]
	v_pk_mul_f32 v[24:25], v[24:25], v[164:165] op_sel_hi:[1,0]
	v_cvt_pk_bf16_f32 v39, v32, v33
	v_add_u32_e32 v32, 0xa0, v140
	v_pk_mul_f32 v[28:29], v[28:29], v[28:29]
	v_pk_mul_f32 v[30:31], v[30:31], v[30:31]
	v_max_f32_e32 v26, 0, v26
	v_max_f32_e32 v27, 0, v27
	v_pk_mul_f32 v[24:25], v[24:25], v[24:25]
	v_max_f32_e32 v20, 0, v20
	v_max_f32_e32 v21, 0, v21
	v_max_f32_e32 v22, 0, v22
;   DI void operator()(const f32x4 (&acc)[2][2][4][2], const pg8::Unit& u, int wr, int wc, int fr_, int fq_) const {
;     ...
;             } else {
;               if (n == 0) {
;                 const f32x4 v1 = acc[ai][bj][m][1];
;                 u32x4 o4;
;                 { const float t0 = fmaxf(v[0], 0.f) * rinv, t1 = fmaxf(v[1], 0.f) * rinv, t2 = fmaxf(v[2], 0.f) * rinv, t3 = fmaxf(v[3], 0.f) * rinv;
;                   o4.x = pack2(t0 * t0, t1 * t1); o4.y = pack2(t2 * t2, t3 * t3); }
;                 { const float t0 = fmaxf(v1[0], 0.f) * rinv, t1 = fmaxf(v1[1], 0.f) * rinv, t2 = fmaxf(v1[2], 0.f) * rinv, t3 = fmaxf(v1[3], 0.f) * rinv;
;                   o4.z = pack2(t0 * t0, t1 * t1); o4.w = pack2(t2 * t2, t3 * t3); }
;                 *(u32x4*)((u16*)big + (size_t)token * 4096 + u.pn * 256 + bj * 128 + wc * 32 + 8 * fq) = o4;
;               }
	v_max_f32_e32 v23, 0, v23
	v_max_f32_e32 v12, 0, v12
	v_max_f32_e32 v13, 0, v13
	v_ashrrev_i32_e32 v33, 31, v32
	v_cvt_pk_bf16_f32 v28, v28, v29
	v_cvt_pk_bf16_f32 v29, v30, v31
	v_cvt_pk_bf16_f32 v30, v24, v25
	v_pk_mul_f32 v[24:25], v[26:27], v[164:165] op_sel_hi:[1,0]
	v_pk_mul_f32 v[20:21], v[20:21], v[164:165] op_sel_hi:[1,0]
	v_pk_mul_f32 v[22:23], v[22:23], v[164:165] op_sel_hi:[1,0]
	v_pk_mul_f32 v[12:13], v[12:13], v[164:165] op_sel_hi:[1,0]
	v_lshlrev_b64 v[32:33], 13, v[32:33]
	v_pk_mul_f32 v[24:25], v[24:25], v[24:25]
	v_pk_mul_f32 v[20:21], v[20:21], v[20:21]
	v_pk_mul_f32 v[22:23], v[22:23], v[22:23]
	v_max_f32_e32 v14, 0, v14
	v_max_f32_e32 v15, 0, v15
	v_pk_mul_f32 v[12:13], v[12:13], v[12:13]
	v_cvt_pk_bf16_f32 v31, v24, v25
	v_lshl_add_u64 v[24:25], s[2:3], 0, v[32:33]
	v_cvt_pk_bf16_f32 v20, v20, v21
	v_cvt_pk_bf16_f32 v21, v22, v23
	v_cvt_pk_bf16_f32 v22, v12, v13
	v_pk_mul_f32 v[12:13], v[14:15], v[164:165] op_sel_hi:[1,0]
	v_lshl_add_u64 v[24:25], v[24:25], 0, s[14:15]
	v_pk_mul_f32 v[12:13], v[12:13], v[12:13]
	v_lshl_add_u64 v[24:25], v[24:25], 0, s[24:25]
	v_cvt_pk_bf16_f32 v23, v12, v13
	v_add_u32_e32 v12, 0xb0, v140
	v_lshl_add_u64 v[24:25], v[24:25], 0, v[144:145]
	v_ashrrev_i32_e32 v13, 31, v12
	v_max_f32_e32 v109, v113, v113
	v_max_f32_e32 v110, v114, v114
	v_max_f32_e32 v111, v115, v115
	v_max_f32_e32 v77, v81, v81
	v_max_f32_e32 v78, v82, v82
	v_max_f32_e32 v79, v83, v83
	v_max_f32_e32 v45, v49, v49
	v_max_f32_e32 v46, v50, v50
	v_max_f32_e32 v47, v51, v51
	global_store_dwordx4 v[24:25], v[20:23], off offset:256
	v_max_f32_e32 v14, v18, v18
	v_max_f32_e32 v15, v19, v19
	v_lshlrev_b64 v[20:21], 13, v[12:13]
	v_max_f32_e32 v12, v16, v16
	v_max_f32_e32 v13, v17, v17
	v_max_f32_e32 v108, 0, v108
	v_max_f32_e32 v109, 0, v109
	v_max_f32_e32 v110, 0, v110
	v_max_f32_e32 v111, 0, v111
	v_max_f32_e32 v104, 0, v104
	v_max_f32_e32 v105, 0, v105
	v_max_f32_e32 v76, 0, v76
	v_max_f32_e32 v77, 0, v77
	v_max_f32_e32 v78, 0, v78
	v_max_f32_e32 v79, 0, v79
	v_max_f32_e32 v72, 0, v72
	v_max_f32_e32 v73, 0, v73
	v_max_f32_e32 v44, 0, v44
	v_max_f32_e32 v45, 0, v45
	v_max_f32_e32 v46, 0, v46
	v_max_f32_e32 v47, 0, v47
	v_max_f32_e32 v40, 0, v40
	v_max_f32_e32 v41, 0, v41
	v_max_f32_e32 v12, 0, v12
	v_max_f32_e32 v13, 0, v13
	v_max_f32_e32 v14, 0, v14
	v_max_f32_e32 v15, 0, v15
	v_mov_b32_e32 v16, v165
	v_max_f32_e32 v8, 0, v8
	v_max_f32_e32 v9, 0, v9
	v_pk_mul_f32 v[108:109], v[108:109], v[112:113] op_sel_hi:[1,0]
	v_pk_mul_f32 v[110:111], v[110:111], v[112:113] op_sel_hi:[1,0]
	v_pk_mul_f32 v[104:105], v[104:105], v[112:113] op_sel_hi:[1,0]
	v_pk_mul_f32 v[76:77], v[76:77], v[80:81] op_sel_hi:[1,0]
	v_pk_mul_f32 v[78:79], v[78:79], v[80:81] op_sel_hi:[1,0]
	v_pk_mul_f32 v[72:73], v[72:73], v[80:81] op_sel_hi:[1,0]
	v_pk_mul_f32 v[44:45], v[44:45], v[48:49] op_sel_hi:[1,0]
	v_pk_mul_f32 v[46:47], v[46:47], v[48:49] op_sel_hi:[1,0]
	v_pk_mul_f32 v[40:41], v[40:41], v[48:49] op_sel_hi:[1,0]
	v_pk_mul_f32 v[12:13], v[12:13], v[16:17] op_sel_hi:[1,0]
	v_pk_mul_f32 v[14:15], v[14:15], v[16:17] op_sel_hi:[1,0]
	v_pk_mul_f32 v[8:9], v[8:9], v[16:17] op_sel_hi:[1,0]
	v_pk_mul_f32 v[108:109], v[108:109], v[108:109]
	v_pk_mul_f32 v[110:111], v[110:111], v[110:111]
	v_max_f32_e32 v106, 0, v106
	v_max_f32_e32 v107, 0, v107
	v_pk_mul_f32 v[104:105], v[104:105], v[104:105]
	v_pk_mul_f32 v[76:77], v[76:77], v[76:77]
	v_pk_mul_f32 v[78:79], v[78:79], v[78:79]
	v_max_f32_e32 v74, 0, v74
	v_max_f32_e32 v75, 0, v75
	v_pk_mul_f32 v[72:73], v[72:73], v[72:73]
	v_pk_mul_f32 v[44:45], v[44:45], v[44:45]
	v_pk_mul_f32 v[46:47], v[46:47], v[46:47]
; template <class Epi, class Sched>
; DI void gemm_phase(LAS unsigned char* lds, const Gemm g, const Sched& S, const Epi& E) {
;     ...
;     E(acc, cur, wr, wc, fr, fq);
;     if (!has_next) break;
; #pragma unroll
;     for (int a = 0; a < 2; ++a)
; #pragma unroll
;       for (int b = 0; b < 2; ++b)
; #pragma unroll
;         for (int m = 0; m < 4; ++m)
; #pragma unroll
;           for (int n = 0; n < 2; ++n) acc[a][b][m][n] = (f32x4){0.f, 0.f, 0.f, 0.f};
;     cur = nxt; cA = nA; cB = nB; ++ui;
;   }
;   DI void operator()(const f32x4 (&acc)[2][2][4][2], const pg8::Unit& u, int wr, int wc, int fr_, int fq_) const {
;     ...
;             } else {
;               if (n == 0) {
;                 const f32x4 v1 = acc[ai][bj][m][1];
;                 u32x4 o4;
;                 { const float t0 = fmaxf(v[0], 0.f) * rinv, t1 = fmaxf(v[1], 0.f) * rinv, t2 = fmaxf(v[2], 0.f) * rinv, t3 = fmaxf(v[3], 0.f) * rinv;
;                   o4.x = pack2(t0 * t0, t1 * t1); o4.y = pack2(t2 * t2, t3 * t3); }
;                 { const float t0 = fmaxf(v1[0], 0.f) * rinv, t1 = fmaxf(v1[1], 0.f) * rinv, t2 = fmaxf(v1[2], 0.f) * rinv, t3 = fmaxf(v1[3], 0.f) * rinv;
;                   o4.z = pack2(t0 * t0, t1 * t1); o4.w = pack2(t2 * t2, t3 * t3); }
;                 *(u32x4*)((u16*)big + (size_t)token * 4096 + u.pn * 256 + bj * 128 + wc * 32 + 8 * fq) = o4;
;               }
	v_max_f32_e32 v42, 0, v42
	v_max_f32_e32 v43, 0, v43
	v_pk_mul_f32 v[40:41], v[40:41], v[40:41]
	v_pk_mul_f32 v[12:13], v[12:13], v[12:13]
	v_pk_mul_f32 v[14:15], v[14:15], v[14:15]
	v_max_f32_e32 v10, 0, v10
	v_max_f32_e32 v11, 0, v11
	v_pk_mul_f32 v[8:9], v[8:9], v[8:9]
	v_cvt_pk_bf16_f32 v108, v108, v109
	v_cvt_pk_bf16_f32 v109, v110, v111
	v_cvt_pk_bf16_f32 v110, v104, v105
	v_pk_mul_f32 v[104:105], v[106:107], v[112:113] op_sel_hi:[1,0]
	v_cvt_pk_bf16_f32 v76, v76, v77
	v_cvt_pk_bf16_f32 v77, v78, v79
	v_cvt_pk_bf16_f32 v78, v72, v73
	v_pk_mul_f32 v[72:73], v[74:75], v[80:81] op_sel_hi:[1,0]
	v_cvt_pk_bf16_f32 v44, v44, v45
	v_cvt_pk_bf16_f32 v45, v46, v47
	v_cvt_pk_bf16_f32 v46, v40, v41
	v_pk_mul_f32 v[40:41], v[42:43], v[48:49] op_sel_hi:[1,0]
	v_cvt_pk_bf16_f32 v12, v12, v13
	v_cvt_pk_bf16_f32 v13, v14, v15
	v_cvt_pk_bf16_f32 v14, v8, v9
	v_pk_mul_f32 v[8:9], v[10:11], v[16:17] op_sel_hi:[1,0]
	v_max_f32_e32 v4, 0, v4
	v_max_f32_e32 v5, 0, v5
	v_max_f32_e32 v6, 0, v6
	v_max_f32_e32 v7, 0, v7
	v_max_f32_e32 v0, 0, v0
	v_max_f32_e32 v1, 0, v1
	v_pk_mul_f32 v[104:105], v[104:105], v[104:105]
	v_pk_mul_f32 v[72:73], v[72:73], v[72:73]
	v_pk_mul_f32 v[40:41], v[40:41], v[40:41]
	v_pk_mul_f32 v[8:9], v[8:9], v[8:9]
	v_pk_mul_f32 v[4:5], v[4:5], v[16:17] op_sel_hi:[1,0]
	v_pk_mul_f32 v[6:7], v[6:7], v[16:17] op_sel_hi:[1,0]
	v_pk_mul_f32 v[0:1], v[0:1], v[16:17] op_sel_hi:[1,0]
	v_cvt_pk_bf16_f32 v111, v104, v105
	v_lshl_add_u64 v[104:105], s[2:3], 0, v[116:117]
	v_cvt_pk_bf16_f32 v79, v72, v73
	v_lshl_add_u64 v[72:73], s[2:3], 0, v[84:85]
	v_cvt_pk_bf16_f32 v47, v40, v41
	v_lshl_add_u64 v[40:41], s[2:3], 0, v[52:53]
	v_cvt_pk_bf16_f32 v15, v8, v9
	v_lshl_add_u64 v[8:9], s[2:3], 0, v[20:21]
	v_pk_mul_f32 v[4:5], v[4:5], v[4:5]
	v_pk_mul_f32 v[6:7], v[6:7], v[6:7]
	v_max_f32_e32 v2, 0, v2
	v_max_f32_e32 v3, 0, v3
	v_pk_mul_f32 v[0:1], v[0:1], v[0:1]
	v_lshl_add_u64 v[104:105], v[104:105], 0, s[14:15]
	v_lshl_add_u64 v[72:73], v[72:73], 0, s[14:15]
	v_lshl_add_u64 v[40:41], v[40:41], 0, s[14:15]
	v_lshl_add_u64 v[8:9], v[8:9], 0, s[14:15]
	v_cvt_pk_bf16_f32 v4, v4, v5
	v_cvt_pk_bf16_f32 v5, v6, v7
	v_cvt_pk_bf16_f32 v6, v0, v1
	v_pk_mul_f32 v[0:1], v[2:3], v[16:17] op_sel_hi:[1,0]
	v_lshl_add_u64 v[104:105], v[104:105], 0, s[24:25]
	v_lshl_add_u64 v[72:73], v[72:73], 0, s[24:25]
	v_lshl_add_u64 v[40:41], v[40:41], 0, s[24:25]
	v_lshl_add_u64 v[8:9], v[8:9], 0, s[24:25]
	v_pk_mul_f32 v[0:1], v[0:1], v[0:1]
	v_lshl_add_u64 v[104:105], v[104:105], 0, v[144:145]
	v_lshl_add_u64 v[72:73], v[72:73], 0, v[144:145]
	v_lshl_add_u64 v[40:41], v[40:41], 0, v[144:145]
	v_lshl_add_u64 v[8:9], v[8:9], 0, v[144:145]
	v_cvt_pk_bf16_f32 v7, v0, v1
	s_and_b64 vcc, exec, s[36:37]
	s_mov_b32 s43, s42
	s_mov_b32 s45, s4
	s_mov_b32 s44, s6
	s_mov_b64 s[16:17], s[12:13]
	s_mov_b64 s[14:15], s[10:11]
	v_readlane_b32 s51, v237, 11
	global_store_dwordx4 v[120:121], v[124:127], off
	global_store_dwordx4 v[104:105], v[108:111], off
	global_store_dwordx4 v[104:105], v[100:103], off offset:256
	global_store_dwordx4 v[88:89], v[92:95], off
	global_store_dwordx4 v[72:73], v[76:79], off
	global_store_dwordx4 v[72:73], v[68:71], off offset:256
	global_store_dwordx4 v[56:57], v[60:63], off
	global_store_dwordx4 v[40:41], v[44:47], off
	global_store_dwordx4 v[40:41], v[36:39], off offset:256
	global_store_dwordx4 v[24:25], v[28:31], off
	global_store_dwordx4 v[8:9], v[12:15], off
	global_store_dwordx4 v[8:9], v[4:7], off offset:256
	s_cbranch_vccz .LBB0_1822
	s_waitcnt vmcnt(0)
	s_cmpk_gt_u32 s9, 0xff
	s_cbranch_scc1 .LBB0_1833
	s_barrier
